# role alternation phases +3/+5 with blocks of 8 units (bit 3)
# speedup vs baseline: 1.0046x; 1.0046x over previous
; #define SUB(k, bit) (!(kargs()->li == 1 && (k) == lo) || ((kargs()->submask >> (bit)) & 1u))
; __global__ void __launch_bounds__(NWAVES * 64, 2) fwd(Args args_unused) {
;     ...
;         if (IN(pb + 3)) {
;             PH_PTRS PH_LAYER
;             if (SUB(pb + 3, 0)) {
.LBB0_1364:
	v_readlane_b32 s99, v254, 3
	s_nop 3
	s_bfe_u32 s99, s99, 0x10003
	s_cmp_eq_u32 s99, 1
	s_cselect_b32 s98, 0, 2
